# prompt scan: one workgroup barrier per two chunks (loaders refill two ring slots per barrier)
# baseline (speedup 1.0000x reference)
; __device__ __forceinline__ void hg_chunk(const LAS unsigned char* sl, f32x4 (&S)[8], float* Orow, int nvalid, int vs, int lane) {
;     const int r = lane & 15, q = lane >> 4;
;     const bf16x8 vfr = *(const LAS bf16x8*)(sl + 16384 + ((vs * 64 + lane) << 4));
;     f32x4 o0 = {0.f, 0.f, 0.f, 0.f}, o1 = {0.f, 0.f, 0.f, 0.f};
;     { const bf16x8 s0 = *(const LAS bf16x8*)(sl + 24576 + (lane << 4)), s1 = *(const LAS bf16x8*)(sl + 24576 + ((64 + lane) << 4));
;       o0 = __builtin_amdgcn_mfma_f32_16x16x32_bf16(s0, vfr, o0, 0, 0, 0); o1 = __builtin_amdgcn_mfma_f32_16x16x32_bf16(s1, vfr, o1, 0, 0, 0); }
; #pragma unroll
;     for (int m = 0; m < 4; ++m) {
;         v4u sw; sw.x = pk2(S[2 * m][0], S[2 * m][1]); sw.y = pk2(S[2 * m][2], S[2 * m][3]); sw.z = pk2(S[2 * m + 1][0], S[2 * m + 1][1]); sw.w = pk2(S[2 * m + 1][2], S[2 * m + 1][3]);
; __device__ __forceinline__ void hg_seq(const Frame& F, unsigned char* ws, const float* s0, float* sout, float* Og, int seq, bool sample, int vs_base, int nvs) {
;     ...
;     for (int n = 0; n < nch; n += 6) {
;         HG_LOAD(R5, n + 5); if (active) hg_chunk(ring, S, Ob + (size_t)(n + 0) * 32 * DA, nvalid, vs, lane); if (n + 1 < nch) HG_STORE(R1, 1); LDSBAR(); if (n + 1 >= nch) break;
;         HG_LOAD(R0, n + 6); if (active) hg_chunk(ring + HG_SLOT, S, Ob + (size_t)(n + 1) * 32 * DA, nvalid, vs, lane); if (n + 2 < nch) HG_STORE(R2, 0); LDSBAR(); if (n + 2 >= nch) break;
;         HG_LOAD(R1, n + 7); if (active) hg_chunk(ring, S, Ob + (size_t)(n + 2) * 32 * DA, nvalid, vs, lane); if (n + 3 < nch) HG_STORE(R3, 1); LDSBAR(); if (n + 3 >= nch) break;
;         HG_LOAD(R2, n + 8); if (active) hg_chunk(ring + HG_SLOT, S, Ob + (size_t)(n + 3) * 32 * DA, nvalid, vs, lane); if (n + 4 < nch) HG_STORE(R4, 0); LDSBAR(); if (n + 4 >= nch) break;
;         HG_LOAD(R3, n + 9); if (active) hg_chunk(ring, S, Ob + (size_t)(n + 4) * 32 * DA, nvalid, vs, lane); if (n + 5 < nch) HG_STORE(R5, 1); LDSBAR(); if (n + 5 >= nch) break;
;         HG_LOAD(R4, n + 10); if (active) hg_chunk(ring + HG_SLOT, S, Ob + (size_t)(n + 5) * 32 * DA, nvalid, vs, lane); if (n + 6 < nch) HG_STORE(R0, 0); LDSBAR();
;     }
;     if (active) {
; #pragma unroll
;     for (int kb = 0; kb < 8; ++kb)
; #pragma unroll
;         for (int i = 0; i < 4; ++i) sout[((size_t)seq * 128 + 16 * kb + 4 * q + i) * 128 + 16 * vs + r] = S[kb][i];
;     }
.Lscan_act_loop:
	v_add_u32_e32 v1, s60, v160
	v_add_u32_e32 v2, s60, v161
	v_add_u32_e32 v3, s60, v163
	ds_read_b128 v[128:131], v3 offset:20480
	ds_read_b128 v[132:135], v3 offset:20544
	ds_read_b128 v[136:139], v3 offset:20608
	ds_read_b128 v[140:143], v3 offset:20672
	ds_read_b128 v[144:147], v3 offset:20736
	ds_read_b128 v[148:151], v3 offset:20800
	ds_read_b128 v[152:155], v3 offset:20864
	ds_read_b128 v[156:159], v3 offset:20928
	ds_read_b128 v[52:55], v2 offset:16384
	ds_read_b128 v[56:59], v1 offset:18432
	ds_read_b128 v[60:63], v1 offset:19456
	ds_read_b128 v[64:67], v1 offset:0
	ds_read_b128 v[80:83], v1 offset:4096
	ds_read_b128 v[68:71], v1 offset:1024
	ds_read_b128 v[84:87], v1 offset:5120
	v_cvt_pk_bf16_f32 v36, v4, v5
	v_cvt_pk_bf16_f32 v37, v6, v7
	v_cvt_pk_bf16_f32 v38, v8, v9
	v_cvt_pk_bf16_f32 v39, v10, v11
	v_cvt_pk_bf16_f32 v40, v12, v13
	v_cvt_pk_bf16_f32 v41, v14, v15
	v_cvt_pk_bf16_f32 v42, v16, v17
	v_cvt_pk_bf16_f32 v43, v18, v19
	v_cvt_pk_bf16_f32 v44, v20, v21
	v_cvt_pk_bf16_f32 v45, v22, v23
	v_cvt_pk_bf16_f32 v46, v24, v25
	v_cvt_pk_bf16_f32 v47, v26, v27
	v_cvt_pk_bf16_f32 v48, v28, v29
	v_cvt_pk_bf16_f32 v49, v30, v31
	v_cvt_pk_bf16_f32 v50, v32, v33
	v_cvt_pk_bf16_f32 v51, v34, v35
	s_waitcnt lgkmcnt(7)
	v_pk_mul_f32 v[4:5], v[4:5], v[128:129]
	v_pk_mul_f32 v[6:7], v[6:7], v[130:131]
	v_pk_mul_f32 v[8:9], v[8:9], v[132:133]
	v_pk_mul_f32 v[10:11], v[10:11], v[134:135]
	v_pk_mul_f32 v[12:13], v[12:13], v[136:137]
	v_pk_mul_f32 v[14:15], v[14:15], v[138:139]
	v_pk_mul_f32 v[16:17], v[16:17], v[140:141]
	v_pk_mul_f32 v[18:19], v[18:19], v[142:143]
	v_pk_mul_f32 v[20:21], v[20:21], v[144:145]
	v_pk_mul_f32 v[22:23], v[22:23], v[146:147]
	v_pk_mul_f32 v[24:25], v[24:25], v[148:149]
	v_pk_mul_f32 v[26:27], v[26:27], v[150:151]
	v_pk_mul_f32 v[28:29], v[28:29], v[152:153]
	v_pk_mul_f32 v[30:31], v[30:31], v[154:155]
	v_pk_mul_f32 v[32:33], v[32:33], v[156:157]
	v_pk_mul_f32 v[34:35], v[34:35], v[158:159]
	ds_read_b128 v[72:75], v1 offset:2048
	ds_read_b128 v[88:91], v1 offset:6144
	ds_read_b128 v[76:79], v1 offset:3072
	ds_read_b128 v[92:95], v1 offset:7168
	ds_read_b128 v[96:99], v1 offset:8192
	ds_read_b128 v[100:103], v1 offset:9216
	ds_read_b128 v[104:107], v1 offset:10240
	ds_read_b128 v[108:111], v1 offset:11264
	ds_read_b128 v[112:115], v1 offset:12288
	ds_read_b128 v[116:119], v1 offset:13312
	ds_read_b128 v[120:123], v1 offset:14336
	ds_read_b128 v[124:127], v1 offset:15360
	s_waitcnt lgkmcnt(15)
	v_mfma_f32_16x16x32_bf16 v[164:167], v[56:59], v[52:55], 0
	v_mfma_f32_16x16x32_bf16 v[168:171], v[60:63], v[52:55], 0
	v_mfma_f32_16x16x32_bf16 v[164:167], v[64:67], v[36:39], v[164:167]
	s_waitcnt lgkmcnt(14)
	v_mfma_f32_16x16x32_bf16 v[168:171], v[80:83], v[36:39], v[168:171]
	s_waitcnt lgkmcnt(13)
	v_mfma_f32_16x16x32_bf16 v[164:167], v[68:71], v[40:43], v[164:167]
	s_waitcnt lgkmcnt(12)
	v_mfma_f32_16x16x32_bf16 v[168:171], v[84:87], v[40:43], v[168:171]
	s_waitcnt lgkmcnt(11)
	v_mfma_f32_16x16x32_bf16 v[164:167], v[72:75], v[44:47], v[164:167]
	s_waitcnt lgkmcnt(10)
	v_mfma_f32_16x16x32_bf16 v[168:171], v[88:91], v[44:47], v[168:171]
	s_waitcnt lgkmcnt(9)
	v_mfma_f32_16x16x32_bf16 v[164:167], v[76:79], v[48:51], v[164:167]
	s_waitcnt lgkmcnt(8)
	v_mfma_f32_16x16x32_bf16 v[168:171], v[92:95], v[48:51], v[168:171]
	s_waitcnt lgkmcnt(7)
	v_mfma_f32_16x16x32_bf16 v[4:7], v[96:99], v[52:55], v[4:7]
	s_waitcnt lgkmcnt(6)
	v_mfma_f32_16x16x32_bf16 v[8:11], v[100:103], v[52:55], v[8:11]
	s_waitcnt lgkmcnt(5)
	v_mfma_f32_16x16x32_bf16 v[12:15], v[104:107], v[52:55], v[12:15]
	s_waitcnt lgkmcnt(4)
	v_mfma_f32_16x16x32_bf16 v[16:19], v[108:111], v[52:55], v[16:19]
	s_waitcnt lgkmcnt(3)
	v_mfma_f32_16x16x32_bf16 v[20:23], v[112:115], v[52:55], v[20:23]
	s_waitcnt lgkmcnt(2)
	v_mfma_f32_16x16x32_bf16 v[24:27], v[116:119], v[52:55], v[24:27]
	s_waitcnt lgkmcnt(1)
	v_mfma_f32_16x16x32_bf16 v[28:31], v[120:123], v[52:55], v[28:31]
	s_waitcnt lgkmcnt(0)
	v_mfma_f32_16x16x32_bf16 v[32:35], v[124:127], v[52:55], v[32:35]
	global_store_dword v172, v164, s[36:37]
	global_store_dword v172, v165, s[36:37] offset:2048
	global_store_dword v173, v166, s[36:37]
	global_store_dword v173, v167, s[36:37] offset:2048
	global_store_dword v174, v168, s[36:37]
	global_store_dword v174, v169, s[36:37] offset:2048
	global_store_dword v175, v170, s[36:37]
	global_store_dword v175, v171, s[36:37] offset:2048
	s_add_u32 s36, s36, 0x10000
	s_addc_u32 s37, s37, 0
	s_add_i32 s60, s60, 21504
	s_cmp_lt_u32 s60, 129024
	s_cselect_b32 s60, s60, 0
	s_add_i32 s62, s62, 1
	s_bitcmp1_b32 s62, 0
	s_cbranch_scc1 .Lscan_act_nobar
	s_waitcnt lgkmcnt(0)
	s_barrier
.Lscan_act_nobar:
	s_cmp_lt_u32 s62, 64
	s_cbranch_scc1 .Lscan_act_loop
	s_nop 7
	s_and_b32 s3, s2, 7
	s_lshl_b32 s3, s3, 2
	s_lshr_b32 s6, s2, 5
	s_add_i32 s3, s3, s6
	s_lshl_b32 s3, s3, 16
	s_add_u32 s6, s20, 0x4400000
	s_addc_u32 s7, s21, 0
	s_add_u32 s6, s6, s3
	s_addc_u32 s7, s7, 0
	global_store_dword v176, v4, s[6:7]
	global_store_dword v176, v5, s[6:7] offset:512
	global_store_dword v176, v6, s[6:7] offset:1024
	global_store_dword v176, v7, s[6:7] offset:1536
	v_add_u32_e32 v176, 0x2000, v176
	global_store_dword v176, v8, s[6:7]
	global_store_dword v176, v9, s[6:7] offset:512
	global_store_dword v176, v10, s[6:7] offset:1024
	global_store_dword v176, v11, s[6:7] offset:1536
	v_add_u32_e32 v176, 0x2000, v176
	global_store_dword v176, v12, s[6:7]
	global_store_dword v176, v13, s[6:7] offset:512
	global_store_dword v176, v14, s[6:7] offset:1024
	global_store_dword v176, v15, s[6:7] offset:1536
	v_add_u32_e32 v176, 0x2000, v176
	global_store_dword v176, v16, s[6:7]
	global_store_dword v176, v17, s[6:7] offset:512
	global_store_dword v176, v18, s[6:7] offset:1024
	global_store_dword v176, v19, s[6:7] offset:1536
	v_add_u32_e32 v176, 0x2000, v176
	global_store_dword v176, v20, s[6:7]
	global_store_dword v176, v21, s[6:7] offset:512
	global_store_dword v176, v22, s[6:7] offset:1024
	global_store_dword v176, v23, s[6:7] offset:1536
	v_add_u32_e32 v176, 0x2000, v176
	global_store_dword v176, v24, s[6:7]
	global_store_dword v176, v25, s[6:7] offset:512
	global_store_dword v176, v26, s[6:7] offset:1024
	global_store_dword v176, v27, s[6:7] offset:1536
	v_add_u32_e32 v176, 0x2000, v176
	global_store_dword v176, v28, s[6:7]
	global_store_dword v176, v29, s[6:7] offset:512
	global_store_dword v176, v30, s[6:7] offset:1024
	global_store_dword v176, v31, s[6:7] offset:1536
	v_add_u32_e32 v176, 0x2000, v176
	global_store_dword v176, v32, s[6:7]
	global_store_dword v176, v33, s[6:7] offset:512
	global_store_dword v176, v34, s[6:7] offset:1024
	global_store_dword v176, v35, s[6:7] offset:1536
	s_branch .Lscan_join

; #define LDSBAR() do { asm volatile("s_waitcnt lgkmcnt(0)" ::: "memory"); __builtin_amdgcn_s_barrier(); asm volatile("" ::: "memory"); } while (0)
; #define HG_STORE(R, s) do { LAS unsigned char* d_ = ring + (s) * HG_SLOT; *(LAS v4u*)(d_ + 16 * tid) = R.q; if (vload) *(LAS v4u*)(d_ + 16384 + 16 * tid) = R.v; *(LAS v4u*)(d_ + 8192 + 16 * tid) = R.l0; \
;         if (tid < 160) *(LAS v4u*)(d_ + 24576 + 16 * tid) = R.l1; } while (0)
; __device__ __forceinline__ void hg_seq(const Frame& F, unsigned char* ws, const float* s0, float* sout, float* Og, int seq, bool sample, int vs_base, int nvs) {
;     ...
;     HgPre R0, R1, R2, R3, R4, R5;
;     R0.l1 = R0.v = (v4u){0u, 0u, 0u, 0u}; R1.l1 = R1.v = (v4u){0u, 0u, 0u, 0u}; R2.l1 = R2.v = (v4u){0u, 0u, 0u, 0u}; R3.l1 = R3.v = (v4u){0u, 0u, 0u, 0u}; R4.l1 = R4.v = (v4u){0u, 0u, 0u, 0u}; R5.l1 = R5.v = (v4u){0u, 0u, 0u, 0u};
;     HG_LOAD(R0, 0); HG_LOAD(R1, 1); HG_LOAD(R2, 2); HG_LOAD(R3, 3); HG_LOAD(R4, 4);
;     HG_STORE(R0, 0); LDSBAR();
;     for (int n = 0; n < nch; n += 6) {
;         HG_LOAD(R5, n + 5); if (active) hg_chunk(ring, S, Ob + (size_t)(n + 0) * 32 * DA, nvalid, vs, lane); if (n + 1 < nch) HG_STORE(R1, 1); LDSBAR(); if (n + 1 >= nch) break;
;         HG_LOAD(R0, n + 6); if (active) hg_chunk(ring + HG_SLOT, S, Ob + (size_t)(n + 1) * 32 * DA, nvalid, vs, lane); if (n + 2 < nch) HG_STORE(R2, 0); LDSBAR(); if (n + 2 >= nch) break;
;         HG_LOAD(R1, n + 7); if (active) hg_chunk(ring, S, Ob + (size_t)(n + 2) * 32 * DA, nvalid, vs, lane); if (n + 3 < nch) HG_STORE(R3, 1); LDSBAR(); if (n + 3 >= nch) break;
;         HG_LOAD(R2, n + 8); if (active) hg_chunk(ring + HG_SLOT, S, Ob + (size_t)(n + 3) * 32 * DA, nvalid, vs, lane); if (n + 4 < nch) HG_STORE(R4, 0); LDSBAR(); if (n + 4 >= nch) break;
;         HG_LOAD(R3, n + 9); if (active) hg_chunk(ring, S, Ob + (size_t)(n + 4) * 32 * DA, nvalid, vs, lane); if (n + 5 < nch) HG_STORE(R5, 1); LDSBAR(); if (n + 5 >= nch) break;
;         HG_LOAD(R4, n + 10); if (active) hg_chunk(ring + HG_SLOT, S, Ob + (size_t)(n + 5) * 32 * DA, nvalid, vs, lane); if (n + 6 < nch) HG_STORE(R0, 0); LDSBAR();
.Lscan_noadv_556:
	s_add_i32 s60, s60, 21504
	s_cmp_lt_u32 s60, 129024
	s_cselect_b32 s60, s60, 0
	s_waitcnt vmcnt(16)
	s_barrier
	s_waitcnt vmcnt(8)
	s_barrier
	s_mov_b32 s62, 1
.Lscan_ld_loop:
	s_add_i32 m0, s60, s46
	s_nop 0
	global_load_lds_dwordx4 v[8:9], off
	s_add_i32 m0, s60, s47
	s_nop 0
	global_load_lds_dwordx4 v[10:11], off
	s_add_i32 m0, s60, s48
	s_nop 0
	global_load_lds_dwordx4 v[12:13], off
	s_add_i32 m0, s60, s49
	s_nop 0
	global_load_lds_dwordx4 v[14:15], off
	s_cmp_lt_u32 s61, 63
	s_cbranch_scc0 .Lscan_noadv_585
	v_lshl_add_u64 v[8:9], v[8:9], 0, s[52:53]
	v_lshl_add_u64 v[10:11], v[10:11], 0, s[54:55]
	v_lshl_add_u64 v[12:13], v[12:13], 0, s[56:57]
	v_lshl_add_u64 v[14:15], v[14:15], 0, s[58:59]
	s_add_i32 s61, s61, 1
.Lscan_noadv_585:
	s_add_i32 s60, s60, 21504
	s_cmp_lt_u32 s60, 129024
	s_cselect_b32 s60, s60, 0
	s_add_i32 m0, s60, s46
	s_nop 0
	global_load_lds_dwordx4 v[8:9], off
	s_add_i32 m0, s60, s47
	s_nop 0
	global_load_lds_dwordx4 v[10:11], off
	s_add_i32 m0, s60, s48
	s_nop 0
	global_load_lds_dwordx4 v[12:13], off
	s_add_i32 m0, s60, s49
	s_nop 0
	global_load_lds_dwordx4 v[14:15], off
	s_cmp_lt_u32 s61, 63
	s_cbranch_scc0 .Lscan_noadv_608
	v_lshl_add_u64 v[8:9], v[8:9], 0, s[52:53]
	v_lshl_add_u64 v[10:11], v[10:11], 0, s[54:55]
	v_lshl_add_u64 v[12:13], v[12:13], 0, s[56:57]
	v_lshl_add_u64 v[14:15], v[14:15], 0, s[58:59]
	s_add_i32 s61, s61, 1
.Lscan_noadv_608:
	s_add_i32 s60, s60, 21504
	s_cmp_lt_u32 s60, 129024
	s_cselect_b32 s60, s60, 0
	s_add_i32 s62, s62, 1
	s_waitcnt vmcnt(8)
	s_barrier
	s_cmp_lt_u32 s62, 32
	s_cbranch_scc1 .Lscan_ld_loop
	s_waitcnt vmcnt(0)
